# grid barrier: arrivals sharded over 8 counter lines + top counter polled (was one contended counter)
# speedup vs baseline: 1.1068x; 1.0551x over previous
.LBB0_112:
	s_or_b64 exec, exec, s[0:1]
	v_lshrrev_b32_e32 v1, 20, v0
	v_lshrrev_b32_e32 v0, 10, v0
	v_or_b32_e32 v0, v0, v1
	s_movk_i32 s0, 0x3ff
	v_and_or_b32 v0, v0, s0, v156
	v_cmp_eq_u32_e32 vcc, 0, v0
	s_barrier
	s_and_saveexec_b64 s[0:1], vcc
	s_cbranch_execz .LBB0_122
	s_cmp_lg_u32 s88, 0
	s_cbranch_scc1 .Lxb_nozero
	v_mov_b32_e32 v2, 0
	v_mov_b32_e32 v1, 0x3c6f0000
	global_atomic_and v1, v2, s[94:95]
	v_mov_b32_e32 v1, 0x3c6f0100
	global_atomic_and v1, v2, s[94:95]
	v_mov_b32_e32 v1, 0x3c6f0200
	global_atomic_and v1, v2, s[94:95]
	v_mov_b32_e32 v1, 0x3c6f0300
	global_atomic_and v1, v2, s[94:95]
	v_mov_b32_e32 v1, 0x3c6f0400
	global_atomic_and v1, v2, s[94:95]
	v_mov_b32_e32 v1, 0x3c6f0500
	global_atomic_and v1, v2, s[94:95]
	v_mov_b32_e32 v1, 0x3c6f0600
	global_atomic_and v1, v2, s[94:95]
	v_mov_b32_e32 v1, 0x3c6f0700
	global_atomic_and v1, v2, s[94:95]
	v_mov_b32_e32 v1, 0x3c6f0800
	global_atomic_and v1, v2, s[94:95]
.Lxb_nozero:
	buffer_wbl2 sc1
	s_waitcnt vmcnt(0)
	s_load_dwordx2 s[4:5], s[40:41], 0x58
	v_mov_b32_e32 v2, 0
	s_mov_b64 s[6:7], exec
	v_mbcnt_lo_u32_b32 v1, s6, 0
	v_mbcnt_hi_u32_b32 v1, s7, v1
	s_waitcnt lgkmcnt(0)
	global_load_dword v0, v2, s[4:5] offset:40
	v_cmp_eq_u32_e32 vcc, 0, v1
	s_and_saveexec_b64 s[12:13], vcc
	s_cbranch_execz .LBB0_115
	s_bcnt1_i32_b64 s2, s[6:7]
	v_mov_b32_e32 v3, s2
	global_atomic_add v3, v2, v3, s[4:5] offset:32 sc0

.LBB0_264:
	s_waitcnt vmcnt(0) lgkmcnt(0)
	s_add_u32 s90, s94, 0x3e280800
	v_writelane_b32 v252, s40, 29
	s_addc_u32 s91, s95, 0
	s_waitcnt lgkmcnt(0)
	v_writelane_b32 v252, s41, 30
	s_barrier
	v_cmp_eq_u32_e64 s[2:3], 0, v156
	s_mov_b64 s[4:5], exec
	s_nop 0
	v_writelane_b32 v252, s2, 31
	s_nop 1
	v_writelane_b32 v252, s3, 32
	s_and_b64 s[2:3], s[4:5], s[2:3]
	s_mov_b64 exec, s[2:3]
	s_cbranch_execz .LBB0_270
	s_mov_b64 s[10:11], exec
	buffer_wbl2 sc1
	s_waitcnt vmcnt(0)
	s_waitcnt vmcnt(0)
	v_mbcnt_lo_u32_b32 v0, s10, 0
	v_mbcnt_hi_u32_b32 v0, s11, v0
	v_cmp_eq_u32_e32 vcc, 0, v0
	s_and_saveexec_b64 s[12:13], vcc
	s_cbranch_execz .LBB0_267
	s_bcnt1_i32_b64 s2, s[10:11]
	s_and_b32 s98, s88, 7
	s_lshl_b32 s98, s98, 8
	s_add_u32 s98, s98, 0x3c6f0000
	v_mov_b32_e32 v0, s98
	v_mov_b32_e32 v1, s2
	global_atomic_add v1, v0, v1, s[94:95] sc0
.LBB0_267:
	s_or_b64 exec, exec, s[12:13]
	s_waitcnt vmcnt(0)
	v_readfirstlane_b32 s99, v1
	v_mov_b32_e32 v0, 0x3c6f0800
	global_load_dword v1, v0, s[94:95] sc1
	s_waitcnt vmcnt(0)
	s_lshr_b32 s100, s96, 3
	s_sub_u32 s100, s100, 1
	s_cmp_lg_u32 s99, s100
	s_cbranch_scc1 .Lxb_0_notlast
	v_mov_b32_e32 v1, 1
	global_atomic_add v0, v1, s[94:95]
.Lxb_0_notlast:
	s_lshr_b32 s100, s96, 6
.Lxb_0_poll:
	global_load_dword v1, v0, s[94:95] sc1
	s_waitcnt vmcnt(0)
	v_cmp_le_u32_e32 vcc, s100, v1
	s_cbranch_vccnz .LBB0_269
	s_sleep 1
	s_branch .Lxb_0_poll

.LBB0_377:
	s_waitcnt vmcnt(0) lgkmcnt(0)
	s_barrier
	s_mov_b64 s[4:5], exec
	v_readlane_b32 s2, v252, 31
	v_readlane_b32 s3, v252, 32
	s_and_b64 s[2:3], s[4:5], s[2:3]
	s_mov_b64 exec, s[2:3]
	s_cbranch_execz .LBB0_383
	v_readlane_b32 s8, v252, 29
	v_readlane_b32 s9, v252, 30
	s_load_dword s3, s[8:9], 0x10
	s_load_dword s2, s[8:9], 0x0
	s_mov_b64 s[10:11], exec
	buffer_wbl2 sc1
	s_waitcnt vmcnt(0) lgkmcnt(0)
	s_waitcnt vmcnt(0)
	v_mbcnt_lo_u32_b32 v0, s10, 0
	v_mbcnt_hi_u32_b32 v0, s11, v0
	s_lshr_b32 s3, s3, 16
	v_cmp_eq_u32_e32 vcc, 0, v0
	s_and_saveexec_b64 s[12:13], vcc
	s_cbranch_execz .LBB0_380
	s_bcnt1_i32_b64 s8, s[10:11]
	s_and_b32 s98, s88, 7
	s_lshl_b32 s98, s98, 8
	s_add_u32 s98, s98, 0x3c6f0000
	v_mov_b32_e32 v0, s98
	v_mov_b32_e32 v1, s8
	global_atomic_add v1, v0, v1, s[94:95] sc0
.LBB0_380:
	s_or_b64 exec, exec, s[12:13]
	s_waitcnt vmcnt(0)
	v_readfirstlane_b32 s99, v1
	v_mov_b32_e32 v0, 0x3c6f0800
	global_load_dword v1, v0, s[94:95] sc1
	s_and_b32 s3, 0xffff, s3
	s_cmp_lg_u32 s3, 0
	s_cselect_b64 s[8:9], -1, 0
	s_cmp_lg_u64 s[8:9], 0
	s_addc_u32 s2, s2, 0
	s_lshl_b32 s2, s2, 1
	s_waitcnt vmcnt(0)
	s_lshr_b32 s100, s2, 3
	s_sub_u32 s100, s100, 1
	s_cmp_lg_u32 s99, s100
	s_cbranch_scc1 .Lxb_1_notlast
	v_mov_b32_e32 v1, 1
	global_atomic_add v0, v1, s[94:95]
.Lxb_1_notlast:
	s_lshr_b32 s100, s2, 6

.LBB0_553:
	s_waitcnt vmcnt(0) lgkmcnt(0)
	s_barrier
	s_mov_b64 s[4:5], exec
	v_readlane_b32 s2, v252, 31
	v_readlane_b32 s3, v252, 32
	s_and_b64 s[2:3], s[4:5], s[2:3]
	v_readlane_b32 s28, v252, 28
	s_mov_b64 exec, s[2:3]
	s_cbranch_execz .LBB0_559
	v_readlane_b32 s8, v252, 29
	v_readlane_b32 s9, v252, 30
	s_load_dword s3, s[8:9], 0x10
	s_load_dword s2, s[8:9], 0x0
	s_mov_b64 s[10:11], exec
	buffer_wbl2 sc1
	s_waitcnt vmcnt(0) lgkmcnt(0)
	s_waitcnt vmcnt(0)
	v_mbcnt_lo_u32_b32 v0, s10, 0
	v_mbcnt_hi_u32_b32 v0, s11, v0
	s_lshr_b32 s3, s3, 16
	v_cmp_eq_u32_e32 vcc, 0, v0
	s_and_saveexec_b64 s[12:13], vcc
	s_cbranch_execz .LBB0_556
	s_bcnt1_i32_b64 s8, s[10:11]
	s_and_b32 s98, s88, 7
	s_lshl_b32 s98, s98, 8
	s_add_u32 s98, s98, 0x3c6f0000
	v_mov_b32_e32 v0, s98
	v_mov_b32_e32 v1, s8
	global_atomic_add v1, v0, v1, s[94:95] sc0
.LBB0_556:
	s_or_b64 exec, exec, s[12:13]
	s_waitcnt vmcnt(0)
	v_readfirstlane_b32 s99, v1
	v_mov_b32_e32 v0, 0x3c6f0800
	global_load_dword v1, v0, s[94:95] sc1
	s_and_b32 s3, 0xffff, s3
	s_cmp_lg_u32 s3, 0
	s_cselect_b64 s[8:9], -1, 0
	s_cmp_lg_u64 s[8:9], 0
	s_addc_u32 s2, s2, 0
	s_mul_i32 s2, s2, 3
	s_waitcnt vmcnt(0)
	s_lshr_b32 s100, s2, 3
	s_sub_u32 s100, s100, 1
	s_cmp_lg_u32 s99, s100
	s_cbranch_scc1 .Lxb_2_notlast
	v_mov_b32_e32 v1, 1
	global_atomic_add v0, v1, s[94:95]

.LBB0_562:
	s_or_b64 exec, exec, s[4:5]
	s_waitcnt vmcnt(0) lgkmcnt(0)
	s_barrier
	s_mov_b64 s[4:5], exec
	v_readlane_b32 s2, v252, 31
	v_readlane_b32 s3, v252, 32
	s_and_b64 s[2:3], s[4:5], s[2:3]
	s_mov_b64 exec, s[2:3]
	s_cbranch_execz .LBB0_568
	s_mov_b64 s[12:13], exec
	buffer_wbl2 sc1
	s_waitcnt vmcnt(0)
	s_waitcnt vmcnt(0)
	v_mbcnt_lo_u32_b32 v0, s12, 0
	v_mbcnt_hi_u32_b32 v0, s13, v0
	v_cmp_eq_u32_e32 vcc, 0, v0
	s_and_saveexec_b64 s[14:15], vcc
	s_cbranch_execz .LBB0_565
	s_bcnt1_i32_b64 s2, s[12:13]
	s_and_b32 s98, s88, 7
	s_lshl_b32 s98, s98, 8
	s_add_u32 s98, s98, 0x3c6f0000
	v_mov_b32_e32 v0, s98
	v_mov_b32_e32 v1, s2
	global_atomic_add v1, v0, v1, s[94:95] sc0
.LBB0_565:
	s_or_b64 exec, exec, s[14:15]
	s_waitcnt vmcnt(0)
	v_readfirstlane_b32 s99, v1
	v_mov_b32_e32 v0, 0x3c6f0800
	global_load_dword v1, v0, s[94:95] sc1
	s_waitcnt vmcnt(0)
	s_lshr_b32 s100, s34, 3
	s_sub_u32 s100, s100, 1
	s_cmp_lg_u32 s99, s100
	s_cbranch_scc1 .Lxb_3_notlast
	v_mov_b32_e32 v1, 1
	global_atomic_add v0, v1, s[94:95]
.Lxb_3_notlast:
	s_lshr_b32 s100, s34, 6

.LBB0_590:
	s_waitcnt vmcnt(0) lgkmcnt(0)
	s_barrier
	s_mov_b64 s[4:5], exec
	v_readlane_b32 s2, v252, 31
	v_readlane_b32 s3, v252, 32
	s_and_b64 s[2:3], s[4:5], s[2:3]
	s_mov_b64 exec, s[2:3]
	s_cbranch_execz .LBB0_596
	s_mov_b64 s[8:9], exec
	buffer_wbl2 sc1
	s_waitcnt vmcnt(0)
	s_waitcnt vmcnt(0)
	v_mbcnt_lo_u32_b32 v0, s8, 0
	v_mbcnt_hi_u32_b32 v0, s9, v0
	v_cmp_eq_u32_e32 vcc, 0, v0
	s_and_saveexec_b64 s[12:13], vcc
	s_cbranch_execz .LBB0_593
	s_bcnt1_i32_b64 s2, s[8:9]
	s_and_b32 s98, s88, 7
	s_lshl_b32 s98, s98, 8
	s_add_u32 s98, s98, 0x3c6f0000
	v_mov_b32_e32 v0, s98
	v_mov_b32_e32 v1, s2
	global_atomic_add v1, v0, v1, s[94:95] sc0
.LBB0_593:
	s_or_b64 exec, exec, s[12:13]
	s_waitcnt vmcnt(0)
	v_readfirstlane_b32 s99, v1
	v_mov_b32_e32 v0, 0x3c6f0800
	global_load_dword v1, v0, s[94:95] sc1
	s_mul_i32 s2, s96, 5
	s_waitcnt vmcnt(0)
	s_lshr_b32 s100, s2, 3
	s_sub_u32 s100, s100, 1
	s_cmp_lg_u32 s99, s100
	s_cbranch_scc1 .Lxb_4_notlast
	v_mov_b32_e32 v1, 1
	global_atomic_add v0, v1, s[94:95]

.LBB0_599:
	s_or_b64 exec, exec, s[4:5]
	s_waitcnt vmcnt(0) lgkmcnt(0)
	s_barrier
	s_mov_b64 s[4:5], exec
	v_readlane_b32 s2, v252, 31
	v_readlane_b32 s3, v252, 32
	s_and_b64 s[2:3], s[4:5], s[2:3]
	s_mov_b64 exec, s[2:3]
	s_cbranch_execz .LBB0_605
	s_mov_b64 s[8:9], exec
	buffer_wbl2 sc1
	s_waitcnt vmcnt(0)
	s_waitcnt vmcnt(0)
	v_mbcnt_lo_u32_b32 v0, s8, 0
	v_mbcnt_hi_u32_b32 v0, s9, v0
	v_cmp_eq_u32_e32 vcc, 0, v0
	s_and_saveexec_b64 s[12:13], vcc
	s_cbranch_execz .LBB0_602
	s_bcnt1_i32_b64 s2, s[8:9]
	s_and_b32 s98, s88, 7
	s_lshl_b32 s98, s98, 8
	s_add_u32 s98, s98, 0x3c6f0000
	v_mov_b32_e32 v0, s98
	v_mov_b32_e32 v1, s2
	global_atomic_add v1, v0, v1, s[94:95] sc0
.LBB0_602:
	s_or_b64 exec, exec, s[12:13]
	s_waitcnt vmcnt(0)
	v_readfirstlane_b32 s99, v1
	v_mov_b32_e32 v0, 0x3c6f0800
	global_load_dword v1, v0, s[94:95] sc1
	s_mul_i32 s2, s96, 6
	s_waitcnt vmcnt(0)
	s_lshr_b32 s100, s2, 3
	s_sub_u32 s100, s100, 1
	s_cmp_lg_u32 s99, s100
	s_cbranch_scc1 .Lxb_5_notlast
	v_mov_b32_e32 v1, 1
	global_atomic_add v0, v1, s[94:95]

.LBB0_611:
	s_waitcnt vmcnt(0) lgkmcnt(0)
	s_barrier
	s_mov_b64 s[2:3], exec
	v_readlane_b32 s4, v252, 31
	v_readlane_b32 s5, v252, 32
	s_and_b64 s[4:5], s[2:3], s[4:5]
	s_mov_b64 exec, s[4:5]
	s_cbranch_execz .LBB0_617
	s_mov_b64 s[4:5], exec
	buffer_wbl2 sc1
	s_waitcnt vmcnt(0)
	s_waitcnt vmcnt(0)
	v_mbcnt_lo_u32_b32 v0, s4, 0
	v_mbcnt_hi_u32_b32 v0, s5, v0
	v_cmp_eq_u32_e32 vcc, 0, v0
	s_and_saveexec_b64 s[8:9], vcc
	s_cbranch_execz .LBB0_614
	s_bcnt1_i32_b64 s4, s[4:5]
	s_and_b32 s98, s88, 7
	s_lshl_b32 s98, s98, 8
	s_add_u32 s98, s98, 0x3c6f0000
	v_mov_b32_e32 v0, s98
	v_mov_b32_e32 v1, s4
	global_atomic_add v1, v0, v1, s[94:95] sc0
.LBB0_614:
	s_or_b64 exec, exec, s[8:9]
	s_waitcnt vmcnt(0)
	v_readfirstlane_b32 s99, v1
	v_mov_b32_e32 v0, 0x3c6f0800
	global_load_dword v1, v0, s[94:95] sc1
	s_mul_i32 s4, s96, 7
	s_waitcnt vmcnt(0)
	s_lshr_b32 s100, s4, 3
	s_sub_u32 s100, s100, 1
	s_cmp_lg_u32 s99, s100
	s_cbranch_scc1 .Lxb_6_notlast
	v_mov_b32_e32 v1, 1
	global_atomic_add v0, v1, s[94:95]
.Lxb_6_notlast:
	s_lshr_b32 s100, s4, 6

.LBB0_627:
	s_waitcnt vmcnt(0) lgkmcnt(0)
	s_barrier
	s_mov_b64 s[2:3], exec
	v_readlane_b32 s4, v252, 31
	v_readlane_b32 s5, v252, 32
	s_and_b64 s[4:5], s[2:3], s[4:5]
	s_mov_b64 exec, s[4:5]
	s_cbranch_execz .LBB0_633
	v_readlane_b32 s12, v252, 29
	v_readlane_b32 s13, v252, 30
	s_load_dword s8, s[12:13], 0x10
	s_nop 0
	s_load_dword s12, s[12:13], 0x0
	s_mov_b64 s[4:5], exec
	buffer_wbl2 sc1
	s_waitcnt vmcnt(0) lgkmcnt(0)
	s_waitcnt vmcnt(0)
	v_mbcnt_lo_u32_b32 v0, s4, 0
	v_mbcnt_hi_u32_b32 v0, s5, v0
	s_lshr_b32 s13, s8, 16
	v_cmp_eq_u32_e32 vcc, 0, v0
	s_and_saveexec_b64 s[8:9], vcc
	s_cbranch_execz .LBB0_630
	s_bcnt1_i32_b64 s4, s[4:5]
	s_and_b32 s98, s88, 7
	s_lshl_b32 s98, s98, 8
	s_add_u32 s98, s98, 0x3c6f0000
	v_mov_b32_e32 v0, s98
	v_mov_b32_e32 v1, s4
	global_atomic_add v1, v0, v1, s[94:95] sc0
.LBB0_630:
	s_or_b64 exec, exec, s[8:9]
	s_waitcnt vmcnt(0)
	v_readfirstlane_b32 s99, v1
	v_mov_b32_e32 v0, 0x3c6f0800
	global_load_dword v1, v0, s[94:95] sc1
	s_and_b32 s4, 0xffff, s13
	s_cmp_lg_u32 s4, 0
	s_cselect_b64 s[4:5], -1, 0
	s_cmp_lg_u64 s[4:5], 0
	s_addc_u32 s4, s12, 0
	s_lshl_b32 s4, s4, 3
	s_waitcnt vmcnt(0)
	s_lshr_b32 s100, s4, 3
	s_sub_u32 s100, s100, 1
	s_cmp_lg_u32 s99, s100
	s_cbranch_scc1 .Lxb_7_notlast
	v_mov_b32_e32 v1, 1
	global_atomic_add v0, v1, s[94:95]

.LBB0_648:
	s_or_b64 exec, exec, s[2:3]
	s_waitcnt vmcnt(0) lgkmcnt(0)
	s_barrier
	s_mov_b64 s[2:3], exec
	v_readlane_b32 s4, v252, 31
	v_readlane_b32 s5, v252, 32
	s_and_b64 s[4:5], s[2:3], s[4:5]
	s_mov_b64 exec, s[4:5]
	s_cbranch_execz .LBB0_654
	s_mov_b64 s[4:5], exec
	buffer_wbl2 sc1
	s_waitcnt vmcnt(0)
	s_waitcnt vmcnt(0)
	v_mbcnt_lo_u32_b32 v0, s4, 0
	v_mbcnt_hi_u32_b32 v0, s5, v0
	v_cmp_eq_u32_e32 vcc, 0, v0
	s_and_saveexec_b64 s[14:15], vcc
	s_cbranch_execz .LBB0_651
	s_bcnt1_i32_b64 s4, s[4:5]
	s_and_b32 s98, s88, 7
	s_lshl_b32 s98, s98, 8
	s_add_u32 s98, s98, 0x3c6f0000
	v_mov_b32_e32 v0, s98
	v_mov_b32_e32 v1, s4
	global_atomic_add v1, v0, v1, s[94:95] sc0
.LBB0_651:
	s_or_b64 exec, exec, s[14:15]
	s_waitcnt vmcnt(0)
	v_readfirstlane_b32 s99, v1
	v_mov_b32_e32 v0, 0x3c6f0800
	global_load_dword v1, v0, s[94:95] sc1
	s_mul_i32 s4, s96, 9
	s_waitcnt vmcnt(0)
	s_lshr_b32 s100, s4, 3
	s_sub_u32 s100, s100, 1
	s_cmp_lg_u32 s99, s100
	s_cbranch_scc1 .Lxb_8_notlast
	v_mov_b32_e32 v1, 1
	global_atomic_add v0, v1, s[94:95]

.LBB0_673:
	s_or_b64 exec, exec, s[2:3]
	s_waitcnt vmcnt(0) lgkmcnt(0)
	s_barrier
	s_mov_b64 s[2:3], exec
	v_readlane_b32 s4, v252, 31
	v_readlane_b32 s5, v252, 32
	s_and_b64 s[4:5], s[2:3], s[4:5]
	s_mov_b64 exec, s[4:5]
	s_cbranch_execz .LBB0_679
	s_mov_b64 s[4:5], exec
	buffer_wbl2 sc1
	s_waitcnt vmcnt(0)
	s_waitcnt vmcnt(0)
	v_mbcnt_lo_u32_b32 v0, s4, 0
	v_mbcnt_hi_u32_b32 v0, s5, v0
	v_cmp_eq_u32_e32 vcc, 0, v0
	s_and_saveexec_b64 s[16:17], vcc
	s_cbranch_execz .LBB0_676
	s_bcnt1_i32_b64 s4, s[4:5]
	s_and_b32 s98, s88, 7
	s_lshl_b32 s98, s98, 8
	s_add_u32 s98, s98, 0x3c6f0000
	v_mov_b32_e32 v0, s98
	v_mov_b32_e32 v1, s4
	global_atomic_add v1, v0, v1, s[94:95] sc0
.LBB0_676:
	s_or_b64 exec, exec, s[16:17]
	s_waitcnt vmcnt(0)
	v_readfirstlane_b32 s99, v1
	v_mov_b32_e32 v0, 0x3c6f0800
	global_load_dword v1, v0, s[94:95] sc1
	s_mul_i32 s4, s96, 10
	s_waitcnt vmcnt(0)
	s_lshr_b32 s100, s4, 3
	s_sub_u32 s100, s100, 1
	s_cmp_lg_u32 s99, s100
	s_cbranch_scc1 .Lxb_9_notlast
	v_mov_b32_e32 v1, 1
	global_atomic_add v0, v1, s[94:95]

.LBB0_698:
	s_or_b64 exec, exec, s[4:5]
	s_waitcnt vmcnt(0) lgkmcnt(0)
	s_barrier
	s_mov_b64 s[4:5], exec
	v_readlane_b32 s16, v252, 31
	v_readlane_b32 s17, v252, 32
	s_and_b64 s[16:17], s[4:5], s[16:17]
	s_mov_b64 exec, s[16:17]
	s_cbranch_execz .LBB0_704
	s_mov_b64 s[16:17], exec
	buffer_wbl2 sc1
	s_waitcnt vmcnt(0)
	s_waitcnt vmcnt(0)
	v_mbcnt_lo_u32_b32 v0, s16, 0
	v_mbcnt_hi_u32_b32 v0, s17, v0
	v_cmp_eq_u32_e32 vcc, 0, v0
	s_and_saveexec_b64 s[18:19], vcc
	s_cbranch_execz .LBB0_701
	s_bcnt1_i32_b64 s16, s[16:17]
	s_and_b32 s98, s88, 7
	s_lshl_b32 s98, s98, 8
	s_add_u32 s98, s98, 0x3c6f0000
	v_mov_b32_e32 v0, s98
	v_mov_b32_e32 v1, s16
	global_atomic_add v1, v0, v1, s[94:95] sc0
.LBB0_701:
	s_or_b64 exec, exec, s[18:19]
	s_waitcnt vmcnt(0)
	v_readfirstlane_b32 s99, v1
	v_mov_b32_e32 v0, 0x3c6f0800
	global_load_dword v1, v0, s[94:95] sc1
	s_mul_i32 s16, s96, 11
	s_waitcnt vmcnt(0)
	s_lshr_b32 s100, s16, 3
	s_sub_u32 s100, s100, 1
	s_cmp_lg_u32 s99, s100
	s_cbranch_scc1 .Lxb_10_notlast
	v_mov_b32_e32 v1, 1
	global_atomic_add v0, v1, s[94:95]
.Lxb_10_notlast:
	s_lshr_b32 s100, s16, 6

.LBB0_722:
	s_or_b64 exec, exec, s[18:19]
	s_waitcnt vmcnt(0)
	v_readfirstlane_b32 s99, v1
	v_mov_b32_e32 v0, 0x3c6f0800
	global_load_dword v1, v0, s[94:95] sc1
	s_mul_i32 s16, s96, 12
	s_waitcnt vmcnt(0)
	s_lshr_b32 s100, s16, 3
	s_sub_u32 s100, s100, 1
	s_cmp_lg_u32 s99, s100
	s_cbranch_scc1 .Lxb_11_notlast
	v_mov_b32_e32 v1, 1
	global_atomic_add v0, v1, s[94:95]

.LBB0_935:
	s_waitcnt vmcnt(0) lgkmcnt(0)
	s_waitcnt lgkmcnt(0)
	s_barrier
	s_mov_b64 s[4:5], exec
	v_readlane_b32 s16, v252, 31
	v_readlane_b32 s17, v252, 32
	s_and_b64 s[16:17], s[4:5], s[16:17]
	s_mov_b64 exec, s[16:17]
	s_cbranch_execz .LBB0_941
	s_mov_b64 s[16:17], exec
	buffer_wbl2 sc1
	s_waitcnt vmcnt(0)
	s_waitcnt vmcnt(0)
	v_mbcnt_lo_u32_b32 v0, s16, 0
	v_mbcnt_hi_u32_b32 v0, s17, v0
	v_cmp_eq_u32_e32 vcc, 0, v0
	s_and_saveexec_b64 s[18:19], vcc
	s_cbranch_execz .LBB0_938
	s_bcnt1_i32_b64 s16, s[16:17]
	s_and_b32 s98, s88, 7
	s_lshl_b32 s98, s98, 8
	s_add_u32 s98, s98, 0x3c6f0000
	v_mov_b32_e32 v0, s98
	v_mov_b32_e32 v1, s16
	global_atomic_add v1, v0, v1, s[94:95] sc0
.LBB0_938:
	s_or_b64 exec, exec, s[18:19]
	s_waitcnt vmcnt(0)
	v_readfirstlane_b32 s99, v1
	v_mov_b32_e32 v0, 0x3c6f0800
	global_load_dword v1, v0, s[94:95] sc1
	s_mul_i32 s16, s96, 13
	s_waitcnt vmcnt(0)
	s_lshr_b32 s100, s16, 3
	s_sub_u32 s100, s100, 1
	s_cmp_lg_u32 s99, s100
	s_cbranch_scc1 .Lxb_12_notlast
	v_mov_b32_e32 v1, 1
	global_atomic_add v0, v1, s[94:95]

.LBB0_989:
	s_waitcnt vmcnt(0) lgkmcnt(0)
	s_barrier
	s_mov_b64 s[4:5], exec
	v_readlane_b32 s8, v252, 31
	v_readlane_b32 s9, v252, 32
	s_and_b64 s[8:9], s[4:5], s[8:9]
	s_mov_b64 exec, s[8:9]
	s_cbranch_execz .LBB0_995
	s_mov_b64 s[8:9], exec
	buffer_wbl2 sc1
	s_waitcnt vmcnt(0)
	s_waitcnt vmcnt(0)
	v_mbcnt_lo_u32_b32 v0, s8, 0
	v_mbcnt_hi_u32_b32 v0, s9, v0
	v_cmp_eq_u32_e32 vcc, 0, v0
	s_and_saveexec_b64 s[16:17], vcc
	s_cbranch_execz .LBB0_992
	s_bcnt1_i32_b64 s8, s[8:9]
	s_and_b32 s98, s88, 7
	s_lshl_b32 s98, s98, 8
	s_add_u32 s98, s98, 0x3c6f0000
	v_mov_b32_e32 v0, s98
	v_mov_b32_e32 v1, s8
	global_atomic_add v1, v0, v1, s[94:95] sc0
.LBB0_992:
	s_or_b64 exec, exec, s[16:17]
	s_waitcnt vmcnt(0)
	v_readfirstlane_b32 s99, v1
	v_mov_b32_e32 v0, 0x3c6f0800
	global_load_dword v1, v0, s[94:95] sc1
	s_mul_i32 s8, s96, 14
	s_waitcnt vmcnt(0)
	s_lshr_b32 s100, s8, 3
	s_sub_u32 s100, s100, 1
	s_cmp_lg_u32 s99, s100
	s_cbranch_scc1 .Lxb_13_notlast
	v_mov_b32_e32 v1, 1
	global_atomic_add v0, v1, s[94:95]
.Lxb_13_notlast:
	s_lshr_b32 s100, s8, 6

.LBB0_1019:
	s_waitcnt vmcnt(0) lgkmcnt(0)
	s_barrier
	s_mov_b64 s[4:5], exec
	v_readlane_b32 s6, v252, 31
	v_readlane_b32 s7, v252, 32
	s_and_b64 s[6:7], s[4:5], s[6:7]
	s_mov_b64 exec, s[6:7]
	s_cbranch_execz .LBB0_1025
	v_readlane_b32 s16, v252, 29
	v_readlane_b32 s17, v252, 30
	s_load_dword s8, s[16:17], 0x10
	s_nop 0
	s_load_dword s16, s[16:17], 0x0
	s_mov_b64 s[6:7], exec
	buffer_wbl2 sc1
	s_waitcnt vmcnt(0) lgkmcnt(0)
	s_waitcnt vmcnt(0)
	v_mbcnt_lo_u32_b32 v0, s6, 0
	v_mbcnt_hi_u32_b32 v0, s7, v0
	s_lshr_b32 s17, s8, 16
	v_cmp_eq_u32_e32 vcc, 0, v0
	s_and_saveexec_b64 s[8:9], vcc
	s_cbranch_execz .LBB0_1022
	s_bcnt1_i32_b64 s6, s[6:7]
	s_and_b32 s98, s88, 7
	s_lshl_b32 s98, s98, 8
	s_add_u32 s98, s98, 0x3c6f0000
	v_mov_b32_e32 v0, s98
	v_mov_b32_e32 v1, s6
	global_atomic_add v1, v0, v1, s[94:95] sc0
.LBB0_1022:
	s_or_b64 exec, exec, s[8:9]
	s_waitcnt vmcnt(0)
	v_readfirstlane_b32 s99, v1
	v_mov_b32_e32 v0, 0x3c6f0800
	global_load_dword v1, v0, s[94:95] sc1
	s_and_b32 s6, 0xffff, s17
	s_cmp_lg_u32 s6, 0
	s_cselect_b64 s[6:7], -1, 0
	s_cmp_lg_u64 s[6:7], 0
	s_addc_u32 s6, s16, 0
	s_mul_i32 s6, s6, 15
	s_waitcnt vmcnt(0)
	s_lshr_b32 s100, s6, 3
	s_sub_u32 s100, s100, 1
	s_cmp_lg_u32 s99, s100
	s_cbranch_scc1 .Lxb_14_notlast
	v_mov_b32_e32 v1, 1
	global_atomic_add v0, v1, s[94:95]
.Lxb_14_notlast:
	s_lshr_b32 s100, s6, 6

.LBB0_1028:
	s_or_b64 exec, exec, s[4:5]
	s_waitcnt vmcnt(0) lgkmcnt(0)
	s_barrier
	s_mov_b64 s[4:5], exec
	v_readlane_b32 s6, v252, 31
	v_readlane_b32 s7, v252, 32
	s_and_b64 s[6:7], s[4:5], s[6:7]
	s_mov_b64 exec, s[6:7]
	s_cbranch_execz .LBB0_1034
	s_mov_b64 s[6:7], exec
	buffer_wbl2 sc1
	s_waitcnt vmcnt(0)
	s_waitcnt vmcnt(0)
	v_mbcnt_lo_u32_b32 v0, s6, 0
	v_mbcnt_hi_u32_b32 v0, s7, v0
	v_cmp_eq_u32_e32 vcc, 0, v0
	s_and_saveexec_b64 s[8:9], vcc
	s_cbranch_execz .LBB0_1031
	s_bcnt1_i32_b64 s6, s[6:7]
	s_and_b32 s98, s88, 7
	s_lshl_b32 s98, s98, 8
	s_add_u32 s98, s98, 0x3c6f0000
	v_mov_b32_e32 v0, s98
	v_mov_b32_e32 v1, s6
	global_atomic_add v1, v0, v1, s[94:95] sc0
.LBB0_1031:
	s_or_b64 exec, exec, s[8:9]
	s_waitcnt vmcnt(0)
	v_readfirstlane_b32 s99, v1
	v_mov_b32_e32 v0, 0x3c6f0800
	global_load_dword v1, v0, s[94:95] sc1
	s_lshl_b32 s6, s96, 4
	s_waitcnt vmcnt(0)
	s_lshr_b32 s100, s6, 3
	s_sub_u32 s100, s100, 1
	s_cmp_lg_u32 s99, s100
	s_cbranch_scc1 .Lxb_15_notlast
	v_mov_b32_e32 v1, 1
	global_atomic_add v0, v1, s[94:95]

.LBB0_1052:
	s_waitcnt vmcnt(0) lgkmcnt(0)
	s_barrier
	s_mov_b64 s[2:3], exec
	v_readlane_b32 s4, v252, 31
	v_readlane_b32 s5, v252, 32
	s_and_b64 s[4:5], s[2:3], s[4:5]
	s_mov_b64 exec, s[4:5]
	s_cbranch_execz .LBB0_1058
	s_mov_b64 s[4:5], exec
	buffer_wbl2 sc1
	s_waitcnt vmcnt(0)
	s_waitcnt vmcnt(0)
	v_mbcnt_lo_u32_b32 v0, s4, 0
	v_mbcnt_hi_u32_b32 v0, s5, v0
	v_cmp_eq_u32_e32 vcc, 0, v0
	s_and_saveexec_b64 s[6:7], vcc
	s_cbranch_execz .LBB0_1055
	s_bcnt1_i32_b64 s4, s[4:5]
	s_and_b32 s98, s88, 7
	s_lshl_b32 s98, s98, 8
	s_add_u32 s98, s98, 0x3c6f0000
	v_mov_b32_e32 v0, s98
	v_mov_b32_e32 v1, s4
	global_atomic_add v1, v0, v1, s[94:95] sc0
.LBB0_1055:
	s_or_b64 exec, exec, s[6:7]
	s_waitcnt vmcnt(0)
	v_readfirstlane_b32 s99, v1
	v_mov_b32_e32 v0, 0x3c6f0800
	global_load_dword v1, v0, s[94:95] sc1
	s_mul_i32 s4, s96, 17
	s_waitcnt vmcnt(0)
	s_lshr_b32 s100, s4, 3
	s_sub_u32 s100, s100, 1
	s_cmp_lg_u32 s99, s100
	s_cbranch_scc1 .Lxb_16_notlast
	v_mov_b32_e32 v1, 1
	global_atomic_add v0, v1, s[94:95]

.LBB0_1061:
	s_or_b64 exec, exec, s[2:3]
	s_waitcnt vmcnt(0) lgkmcnt(0)
	s_barrier
	s_mov_b64 s[2:3], exec
	v_readlane_b32 s4, v252, 31
	v_readlane_b32 s5, v252, 32
	s_and_b64 s[4:5], s[2:3], s[4:5]
	s_mov_b64 exec, s[4:5]
	s_cbranch_execz .LBB0_1067
	s_mov_b64 s[4:5], exec
	buffer_wbl2 sc1
	s_waitcnt vmcnt(0)
	s_waitcnt vmcnt(0)
	v_mbcnt_lo_u32_b32 v0, s4, 0
	v_mbcnt_hi_u32_b32 v0, s5, v0
	v_cmp_eq_u32_e32 vcc, 0, v0
	s_and_saveexec_b64 s[6:7], vcc
	s_cbranch_execz .LBB0_1064
	s_bcnt1_i32_b64 s4, s[4:5]
	s_and_b32 s98, s88, 7
	s_lshl_b32 s98, s98, 8
	s_add_u32 s98, s98, 0x3c6f0000
	v_mov_b32_e32 v0, s98
	v_mov_b32_e32 v1, s4
	global_atomic_add v1, v0, v1, s[94:95] sc0
.LBB0_1064:
	s_or_b64 exec, exec, s[6:7]
	s_waitcnt vmcnt(0)
	v_readfirstlane_b32 s99, v1
	v_mov_b32_e32 v0, 0x3c6f0800
	global_load_dword v1, v0, s[94:95] sc1
	s_mul_i32 s4, s96, 18
	s_waitcnt vmcnt(0)
	s_lshr_b32 s100, s4, 3
	s_sub_u32 s100, s100, 1
	s_cmp_lg_u32 s99, s100
	s_cbranch_scc1 .Lxb_17_notlast
	v_mov_b32_e32 v1, 1
	global_atomic_add v0, v1, s[94:95]

.LBB0_1076:
	s_or_b64 exec, exec, s[6:7]
	s_waitcnt vmcnt(0)
	v_readfirstlane_b32 s99, v1
	v_mov_b32_e32 v0, 0x3c6f0800
	global_load_dword v1, v0, s[94:95] sc1
	s_mul_i32 s4, s96, 19
	s_waitcnt vmcnt(0)
	s_lshr_b32 s100, s4, 3
	s_sub_u32 s100, s100, 1
	s_cmp_lg_u32 s99, s100
	s_cbranch_scc1 .Lxb_18_notlast
	v_mov_b32_e32 v1, 1
	global_atomic_add v0, v1, s[94:95]

.LBB0_1089:
	s_waitcnt vmcnt(0) lgkmcnt(0)
	s_barrier
	s_mov_b64 s[0:1], exec
	v_readlane_b32 s2, v252, 31
	v_readlane_b32 s3, v252, 32
	s_and_b64 s[2:3], s[0:1], s[2:3]
	s_mov_b64 exec, s[2:3]
	s_cbranch_execz .LBB0_1095
	v_readlane_b32 s8, v252, 29
	v_readlane_b32 s9, v252, 30
	s_load_dword s4, s[8:9], 0x10
	s_load_dword s6, s[8:9], 0x0
	s_mov_b64 s[2:3], exec
	buffer_wbl2 sc1
	s_waitcnt vmcnt(0) lgkmcnt(0)
	s_waitcnt vmcnt(0)
	v_mbcnt_lo_u32_b32 v0, s2, 0
	v_mbcnt_hi_u32_b32 v0, s3, v0
	s_lshr_b32 s7, s4, 16
	v_cmp_eq_u32_e32 vcc, 0, v0
	s_and_saveexec_b64 s[4:5], vcc
	s_cbranch_execz .LBB0_1092
	s_bcnt1_i32_b64 s2, s[2:3]
	s_and_b32 s98, s88, 7
	s_lshl_b32 s98, s98, 8
	s_add_u32 s98, s98, 0x3c6f0000
	v_mov_b32_e32 v0, s98
	v_mov_b32_e32 v1, s2
	global_atomic_add v1, v0, v1, s[94:95] sc0
.LBB0_1092:
	s_or_b64 exec, exec, s[4:5]
	s_waitcnt vmcnt(0)
	v_readfirstlane_b32 s99, v1
	v_mov_b32_e32 v0, 0x3c6f0800
	global_load_dword v1, v0, s[94:95] sc1
	s_and_b32 s2, 0xffff, s7
	s_cmp_lg_u32 s2, 0
	s_cselect_b64 s[2:3], -1, 0
	s_cmp_lg_u64 s[2:3], 0
	s_addc_u32 s2, s6, 0
	s_mul_i32 s2, s2, 20
	s_waitcnt vmcnt(0)
	s_lshr_b32 s100, s2, 3
	s_sub_u32 s100, s100, 1
	s_cmp_lg_u32 s99, s100
	s_cbranch_scc1 .Lxb_19_notlast
	v_mov_b32_e32 v1, 1
	global_atomic_add v0, v1, s[94:95]

.LBB0_1110:
	s_or_b64 exec, exec, s[0:1]
	s_waitcnt vmcnt(0) lgkmcnt(0)
	s_barrier
	s_mov_b64 s[0:1], exec
	v_readlane_b32 s2, v252, 31
	v_readlane_b32 s3, v252, 32
	s_and_b64 s[2:3], s[0:1], s[2:3]
	s_mov_b64 exec, s[2:3]
	s_cbranch_execz .LBB0_1116
	s_mov_b64 s[2:3], exec
	buffer_wbl2 sc1
	s_waitcnt vmcnt(0)
	s_waitcnt vmcnt(0)
	v_mbcnt_lo_u32_b32 v0, s2, 0
	v_mbcnt_hi_u32_b32 v0, s3, v0
	v_cmp_eq_u32_e32 vcc, 0, v0
	s_and_saveexec_b64 s[4:5], vcc
	s_cbranch_execz .LBB0_1113
	s_bcnt1_i32_b64 s2, s[2:3]
	s_and_b32 s98, s88, 7
	s_lshl_b32 s98, s98, 8
	s_add_u32 s98, s98, 0x3c6f0000
	v_mov_b32_e32 v0, s98
	v_mov_b32_e32 v1, s2
	global_atomic_add v1, v0, v1, s[94:95] sc0
.LBB0_1113:
	s_or_b64 exec, exec, s[4:5]
	s_waitcnt vmcnt(0)
	v_readfirstlane_b32 s99, v1
	v_mov_b32_e32 v0, 0x3c6f0800
	global_load_dword v1, v0, s[94:95] sc1
	s_mul_i32 s2, s96, 21
	s_waitcnt vmcnt(0)
	s_lshr_b32 s100, s2, 3
	s_sub_u32 s100, s100, 1
	s_cmp_lg_u32 s99, s100
	s_cbranch_scc1 .Lxb_20_notlast
	v_mov_b32_e32 v1, 1
	global_atomic_add v0, v1, s[94:95]

.LBB0_1138:
	s_or_b64 exec, exec, s[4:5]
	s_waitcnt vmcnt(0)
	v_readfirstlane_b32 s99, v1
	v_mov_b32_e32 v0, 0x3c6f0800
	global_load_dword v1, v0, s[94:95] sc1
	s_mul_i32 s2, s96, 22
	s_waitcnt vmcnt(0)
	s_lshr_b32 s100, s2, 3
	s_sub_u32 s100, s100, 1
	s_cmp_lg_u32 s99, s100
	s_cbranch_scc1 .Lxb_21_notlast
	v_mov_b32_e32 v1, 1
	global_atomic_add v0, v1, s[94:95]

.LBB0_1163:
	s_or_b64 exec, exec, s[4:5]
	s_waitcnt vmcnt(0)
	v_readfirstlane_b32 s99, v1
	v_mov_b32_e32 v0, 0x3c6f0800
	global_load_dword v1, v0, s[94:95] sc1
	s_mul_i32 s2, s96, 23
	s_waitcnt vmcnt(0)
	s_lshr_b32 s100, s2, 3
	s_sub_u32 s100, s100, 1
	s_cmp_lg_u32 s99, s100
	s_cbranch_scc1 .Lxb_22_notlast
	v_mov_b32_e32 v1, 1
	global_atomic_add v0, v1, s[94:95]
